# filter GEMM epilogue: per-row delta hoisted to a lane vector + readlane broadcast, SGPR-base stores; hyin GEMM k-loop on 3-stage LDS-DMA ring
# speedup vs baseline: 1.0105x; 1.0105x over previous
.LBB0_361:
	s_mul_hi_i32 s0, s23, 0x2aaaaaab
	s_lshr_b32 s1, s0, 31
	s_ashr_i32 s0, s0, 1
	s_add_i32 s20, s0, s1
	s_mul_i32 s0, s20, 12
	s_sub_i32 s0, s23, s0
	s_lshl_b32 s40, s0, 8
	s_lshl_b32 s42, s20, 7
	s_ashr_i32 s41, s40, 31
	s_ashr_i32 s43, s42, 31
	s_lshl_b64 s[0:1], s[40:41], 11
	s_lshl_b64 s[20:21], s[42:43], 11
	s_add_u32 s0, s24, s0
	v_readlane_b32 s4, v254, 0
	s_addc_u32 s1, s25, s1
	v_readlane_b32 s6, v254, 2
	v_readlane_b32 s7, v254, 3
	s_add_u32 s20, s6, s20
	s_addc_u32 s21, s7, s21
	s_waitcnt lgkmcnt(0)
	v_lshrrev_b32_e32 v115, 3, v196
	v_lshrrev_b32_e32 v116, 4, v196
	v_xor_b32_e32 v116, v116, v196
	v_and_b32_e32 v116, 7, v116
	v_lshlrev_b32_e32 v116, 4, v116
	v_lshl_or_b32 v98, v115, 11, v116
	v_add_u32_e32 v99, 0x20000, v98
	v_add_u32_e32 v100, 0x40000, v98
	v_add_u32_e32 v101, 0x60000, v98
	v_add_u32_e32 v115, 0, v110
	v_xor_b32_e32 v115, v115, v111
	v_lshlrev_b32_e32 v115, 4, v115
	v_add3_u32 v102, v122, v115, 0
	v_add3_u32 v106, v123, v115, 0
	v_add_u32_e32 v115, 2, v110
	v_xor_b32_e32 v115, v115, v111
	v_lshlrev_b32_e32 v115, 4, v115
	v_add3_u32 v103, v122, v115, 0
	v_add3_u32 v107, v123, v115, 0
	v_add_u32_e32 v115, 4, v110
	v_xor_b32_e32 v115, v115, v111
	v_lshlrev_b32_e32 v115, 4, v115
	v_add3_u32 v104, v122, v115, 0
	v_add3_u32 v108, v123, v115, 0
	v_add_u32_e32 v115, 6, v110
	v_xor_b32_e32 v115, v115, v111
	v_lshlrev_b32_e32 v115, 4, v115
	v_add3_u32 v105, v122, v115, 0
	v_add3_u32 v109, v123, v115, 0
	v_lshrrev_b32_e32 v115, 6, v196
	v_mov_b64_e32 v[2:3], 0
	v_mov_b64_e32 v[4:5], 0
	v_mov_b64_e32 v[6:7], 0
	v_mov_b64_e32 v[8:9], 0
	v_mov_b64_e32 v[10:11], 0
	v_mov_b64_e32 v[12:13], 0
	v_mov_b64_e32 v[14:15], 0
	v_mov_b64_e32 v[16:17], 0
	v_mov_b64_e32 v[18:19], 0
	v_mov_b64_e32 v[20:21], 0
	v_mov_b64_e32 v[22:23], 0
	v_mov_b64_e32 v[24:25], 0
	v_mov_b64_e32 v[26:27], 0
	v_mov_b64_e32 v[28:29], 0
	v_mov_b64_e32 v[30:31], 0
	v_mov_b64_e32 v[32:33], 0
	v_mov_b64_e32 v[34:35], 0
	v_mov_b64_e32 v[36:37], 0
	v_mov_b64_e32 v[38:39], 0
	v_mov_b64_e32 v[40:41], 0
	v_mov_b64_e32 v[42:43], 0
	v_mov_b64_e32 v[44:45], 0
	v_mov_b64_e32 v[46:47], 0
	v_mov_b64_e32 v[48:49], 0
	v_mov_b64_e32 v[50:51], 0
	v_mov_b64_e32 v[52:53], 0
	v_mov_b64_e32 v[54:55], 0
	v_mov_b64_e32 v[56:57], 0
	v_mov_b64_e32 v[58:59], 0
	v_mov_b64_e32 v[60:61], 0
	v_mov_b64_e32 v[62:63], 0
	v_mov_b64_e32 v[64:65], 0
	v_readfirstlane_b32 s30, v115
	s_lshl_b32 s30, s30, 10
	s_add_i32 s30, s30, 16
	s_add_i32 vcc_hi, s30, 0xc000
	s_mov_b32 m0, s30
	s_nop 0
	global_load_lds_dwordx4 v98, s[0:1]
	s_add_u32 m0, m0, 0x2000
	s_nop 0
	global_load_lds_dwordx4 v99, s[0:1]
	s_add_u32 m0, m0, 0x2000
	s_nop 0
	global_load_lds_dwordx4 v100, s[0:1]
	s_add_u32 m0, m0, 0x2000
	s_nop 0
	global_load_lds_dwordx4 v101, s[0:1]
	s_add_u32 m0, m0, 0x2000
	s_nop 0
	global_load_lds_dwordx4 v98, s[20:21]
	s_add_u32 m0, m0, 0x2000
	s_nop 0
	global_load_lds_dwordx4 v99, s[20:21]
	s_add_u32 s0, s0, 0x80
	s_addc_u32 s1, s1, 0
	s_add_u32 s20, s20, 0x80
	s_addc_u32 s21, s21, 0
	s_mov_b32 m0, vcc_hi
	s_nop 0
	global_load_lds_dwordx4 v98, s[0:1]
	s_add_u32 m0, m0, 0x2000
	s_nop 0
	global_load_lds_dwordx4 v99, s[0:1]
	s_add_u32 m0, m0, 0x2000
	s_nop 0
	global_load_lds_dwordx4 v100, s[0:1]
	s_add_u32 m0, m0, 0x2000
	s_nop 0
	global_load_lds_dwordx4 v101, s[0:1]
	s_add_u32 m0, m0, 0x2000
	s_nop 0
	global_load_lds_dwordx4 v98, s[20:21]
	s_add_u32 m0, m0, 0x2000
	s_nop 0
	global_load_lds_dwordx4 v99, s[20:21]
	s_add_u32 s0, s0, 0x80
	s_addc_u32 s1, s1, 0
	s_add_u32 s20, s20, 0x80
	s_addc_u32 s21, s21, 0
	s_mov_b32 s27, 0
	s_movk_i32 s26, 14
.Lhyin_loop:
	s_waitcnt vmcnt(6)
	s_barrier
	s_add_i32 vcc_hi, s27, 2
	s_cmp_ge_u32 vcc_hi, 3
	s_cselect_b32 vcc_lo, 3, 0
	s_sub_i32 vcc_hi, vcc_hi, vcc_lo
	s_mul_i32 vcc_hi, vcc_hi, 0xc000
	s_add_i32 vcc_hi, vcc_hi, s30
	ds_read_b128 v[66:69], v102
	ds_read_b128 v[70:73], v102 offset:4096
	ds_read_b128 v[74:77], v106 offset:32768
	ds_read_b128 v[78:81], v106 offset:36864
	ds_read_b128 v[82:85], v103
	ds_read_b128 v[86:89], v103 offset:4096
	ds_read_b128 v[90:93], v107 offset:32768
	ds_read_b128 v[94:97], v107 offset:36864
	s_waitcnt lgkmcnt(4)
	s_setprio 1
	v_mfma_f32_32x32x16_bf16 v[2:17], v[66:69], v[74:77], v[2:17]
	s_mov_b32 m0, vcc_hi
	v_mfma_f32_32x32x16_bf16 v[18:33], v[70:73], v[74:77], v[18:33]
	global_load_lds_dwordx4 v98, s[0:1]
	s_add_u32 m0, m0, 0x2000
	v_mfma_f32_32x32x16_bf16 v[34:49], v[66:69], v[78:81], v[34:49]
	global_load_lds_dwordx4 v99, s[0:1]
	s_add_u32 m0, m0, 0x2000
	v_mfma_f32_32x32x16_bf16 v[50:65], v[70:73], v[78:81], v[50:65]
	global_load_lds_dwordx4 v100, s[0:1]
	s_add_u32 m0, m0, 0x2000
	s_nop 0
	global_load_lds_dwordx4 v101, s[0:1]
	s_add_u32 m0, m0, 0x2000
	s_nop 0
	global_load_lds_dwordx4 v98, s[20:21]
	s_add_u32 m0, m0, 0x2000
	s_nop 0
	global_load_lds_dwordx4 v99, s[20:21]
	s_add_u32 s0, s0, 0x80
	s_addc_u32 s1, s1, 0
	s_add_u32 s20, s20, 0x80
	s_addc_u32 s21, s21, 0
	s_setprio 0
	ds_read_b128 v[66:69], v104
	ds_read_b128 v[70:73], v104 offset:4096
	ds_read_b128 v[74:77], v108 offset:32768
	ds_read_b128 v[78:81], v108 offset:36864
	s_waitcnt lgkmcnt(4)
	s_setprio 1
	v_mfma_f32_32x32x16_bf16 v[2:17], v[82:85], v[90:93], v[2:17]
	v_mfma_f32_32x32x16_bf16 v[18:33], v[86:89], v[90:93], v[18:33]
	v_mfma_f32_32x32x16_bf16 v[34:49], v[82:85], v[94:97], v[34:49]
	v_mfma_f32_32x32x16_bf16 v[50:65], v[86:89], v[94:97], v[50:65]
	s_setprio 0
	ds_read_b128 v[82:85], v105
	ds_read_b128 v[86:89], v105 offset:4096
	ds_read_b128 v[90:93], v109 offset:32768
	ds_read_b128 v[94:97], v109 offset:36864
	s_waitcnt lgkmcnt(4)
	s_setprio 1
	v_mfma_f32_32x32x16_bf16 v[2:17], v[66:69], v[74:77], v[2:17]
	v_mfma_f32_32x32x16_bf16 v[18:33], v[70:73], v[74:77], v[18:33]
	v_mfma_f32_32x32x16_bf16 v[34:49], v[66:69], v[78:81], v[34:49]
	v_mfma_f32_32x32x16_bf16 v[50:65], v[70:73], v[78:81], v[50:65]
	s_setprio 0
	s_waitcnt lgkmcnt(0)
	s_setprio 1
	v_mfma_f32_32x32x16_bf16 v[2:17], v[82:85], v[90:93], v[2:17]
	v_mfma_f32_32x32x16_bf16 v[18:33], v[86:89], v[90:93], v[18:33]
	v_mfma_f32_32x32x16_bf16 v[34:49], v[82:85], v[94:97], v[34:49]
	v_mfma_f32_32x32x16_bf16 v[50:65], v[86:89], v[94:97], v[50:65]
	s_setprio 0
	s_add_i32 s27, s27, 1
	s_cmp_eq_u32 s27, 3
	s_cselect_b32 vcc_lo, 0xfffdc000, 0
	s_cselect_b32 s27, 0, s27
	s_add_i32 vcc_lo, vcc_lo, 0xc000
	v_add_u32_e32 v102, vcc_lo, v102
	v_add_u32_e32 v106, vcc_lo, v106
	v_add_u32_e32 v103, vcc_lo, v103
	v_add_u32_e32 v107, vcc_lo, v107
	v_add_u32_e32 v104, vcc_lo, v104
	v_add_u32_e32 v108, vcc_lo, v108
	v_add_u32_e32 v105, vcc_lo, v105
	v_add_u32_e32 v109, vcc_lo, v109
	s_add_i32 s26, s26, -1
	s_cmp_lg_u32 s26, 0
	s_cbranch_scc1 .Lhyin_loop
	s_waitcnt vmcnt(6)
	s_barrier
	ds_read_b128 v[66:69], v102
	ds_read_b128 v[70:73], v102 offset:4096
	ds_read_b128 v[74:77], v106 offset:32768
	ds_read_b128 v[78:81], v106 offset:36864
	ds_read_b128 v[82:85], v103
	ds_read_b128 v[86:89], v103 offset:4096
	ds_read_b128 v[90:93], v107 offset:32768
	ds_read_b128 v[94:97], v107 offset:36864
	s_waitcnt lgkmcnt(4)
	s_setprio 1
	v_mfma_f32_32x32x16_bf16 v[2:17], v[66:69], v[74:77], v[2:17]
	v_mfma_f32_32x32x16_bf16 v[18:33], v[70:73], v[74:77], v[18:33]
	v_mfma_f32_32x32x16_bf16 v[34:49], v[66:69], v[78:81], v[34:49]
	v_mfma_f32_32x32x16_bf16 v[50:65], v[70:73], v[78:81], v[50:65]
	s_setprio 0
	ds_read_b128 v[66:69], v104
	ds_read_b128 v[70:73], v104 offset:4096
	ds_read_b128 v[74:77], v108 offset:32768
	ds_read_b128 v[78:81], v108 offset:36864
	s_waitcnt lgkmcnt(4)
	s_setprio 1
	v_mfma_f32_32x32x16_bf16 v[2:17], v[82:85], v[90:93], v[2:17]
	v_mfma_f32_32x32x16_bf16 v[18:33], v[86:89], v[90:93], v[18:33]
	v_mfma_f32_32x32x16_bf16 v[34:49], v[82:85], v[94:97], v[34:49]
	v_mfma_f32_32x32x16_bf16 v[50:65], v[86:89], v[94:97], v[50:65]
	s_setprio 0
	ds_read_b128 v[82:85], v105
	ds_read_b128 v[86:89], v105 offset:4096
	ds_read_b128 v[90:93], v109 offset:32768
	ds_read_b128 v[94:97], v109 offset:36864
	s_waitcnt lgkmcnt(4)
	s_setprio 1
	v_mfma_f32_32x32x16_bf16 v[2:17], v[66:69], v[74:77], v[2:17]
	v_mfma_f32_32x32x16_bf16 v[18:33], v[70:73], v[74:77], v[18:33]
	v_mfma_f32_32x32x16_bf16 v[34:49], v[66:69], v[78:81], v[34:49]
	v_mfma_f32_32x32x16_bf16 v[50:65], v[70:73], v[78:81], v[50:65]
	s_setprio 0
	s_waitcnt lgkmcnt(0)
	s_setprio 1
	v_mfma_f32_32x32x16_bf16 v[2:17], v[82:85], v[90:93], v[2:17]
	v_mfma_f32_32x32x16_bf16 v[18:33], v[86:89], v[90:93], v[18:33]
	v_mfma_f32_32x32x16_bf16 v[34:49], v[82:85], v[94:97], v[34:49]
	v_mfma_f32_32x32x16_bf16 v[50:65], v[86:89], v[94:97], v[50:65]
	s_setprio 0
	s_add_i32 s27, s27, 1
	s_cmp_eq_u32 s27, 3
	s_cselect_b32 vcc_lo, 0xfffdc000, 0
	s_cselect_b32 s27, 0, s27
	s_add_i32 vcc_lo, vcc_lo, 0xc000
	v_add_u32_e32 v102, vcc_lo, v102
	v_add_u32_e32 v106, vcc_lo, v106
	v_add_u32_e32 v103, vcc_lo, v103
	v_add_u32_e32 v107, vcc_lo, v107
	v_add_u32_e32 v104, vcc_lo, v104
	v_add_u32_e32 v108, vcc_lo, v108
	v_add_u32_e32 v105, vcc_lo, v105
	v_add_u32_e32 v109, vcc_lo, v109
	s_waitcnt vmcnt(0)
	s_barrier
	ds_read_b128 v[66:69], v102
	ds_read_b128 v[70:73], v102 offset:4096
	ds_read_b128 v[74:77], v106 offset:32768
	ds_read_b128 v[78:81], v106 offset:36864
	ds_read_b128 v[82:85], v103
	ds_read_b128 v[86:89], v103 offset:4096
	ds_read_b128 v[90:93], v107 offset:32768
	ds_read_b128 v[94:97], v107 offset:36864
	s_waitcnt lgkmcnt(4)
	s_setprio 1
	v_mfma_f32_32x32x16_bf16 v[2:17], v[66:69], v[74:77], v[2:17]
	v_mfma_f32_32x32x16_bf16 v[18:33], v[70:73], v[74:77], v[18:33]
	v_mfma_f32_32x32x16_bf16 v[34:49], v[66:69], v[78:81], v[34:49]
	v_mfma_f32_32x32x16_bf16 v[50:65], v[70:73], v[78:81], v[50:65]
	s_setprio 0
	ds_read_b128 v[66:69], v104
	ds_read_b128 v[70:73], v104 offset:4096
	ds_read_b128 v[74:77], v108 offset:32768
	ds_read_b128 v[78:81], v108 offset:36864
	s_waitcnt lgkmcnt(4)
	s_setprio 1
	v_mfma_f32_32x32x16_bf16 v[2:17], v[82:85], v[90:93], v[2:17]
	v_mfma_f32_32x32x16_bf16 v[18:33], v[86:89], v[90:93], v[18:33]
	v_mfma_f32_32x32x16_bf16 v[34:49], v[82:85], v[94:97], v[34:49]
	v_mfma_f32_32x32x16_bf16 v[50:65], v[86:89], v[94:97], v[50:65]
	s_setprio 0
	ds_read_b128 v[82:85], v105
	ds_read_b128 v[86:89], v105 offset:4096
	ds_read_b128 v[90:93], v109 offset:32768
	ds_read_b128 v[94:97], v109 offset:36864
	s_waitcnt lgkmcnt(4)
	s_setprio 1
	v_mfma_f32_32x32x16_bf16 v[2:17], v[66:69], v[74:77], v[2:17]
	v_mfma_f32_32x32x16_bf16 v[18:33], v[70:73], v[74:77], v[18:33]
	v_mfma_f32_32x32x16_bf16 v[34:49], v[66:69], v[78:81], v[34:49]
	v_mfma_f32_32x32x16_bf16 v[50:65], v[70:73], v[78:81], v[50:65]
	s_setprio 0
	s_waitcnt lgkmcnt(0)
	s_setprio 1
	v_mfma_f32_32x32x16_bf16 v[2:17], v[82:85], v[90:93], v[2:17]
	v_mfma_f32_32x32x16_bf16 v[18:33], v[86:89], v[90:93], v[18:33]
	v_mfma_f32_32x32x16_bf16 v[34:49], v[82:85], v[94:97], v[34:49]
	v_mfma_f32_32x32x16_bf16 v[50:65], v[86:89], v[94:97], v[50:65]
	s_setprio 0
	s_barrier
	v_readlane_b32 s5, v254, 1
	v_readlane_b32 s8, v254, 4
	v_readlane_b32 s9, v254, 5
	v_readlane_b32 s10, v254, 6
	v_readlane_b32 s11, v254, 7
	v_readlane_b32 s12, v254, 8
	v_readlane_b32 s13, v254, 9
	v_readlane_b32 s14, v254, 10
	v_readlane_b32 s15, v254, 11
	v_readlane_b32 s16, v254, 12
	v_readlane_b32 s17, v254, 13
	v_readlane_b32 s18, v254, 14
	v_readlane_b32 s19, v254, 15
	s_nop 7
	s_barrier
	s_nop 5
	ds_write2_b32 v119, v2, v34 offset1:32
	ds_write2_b32 v119, v3, v35 offset0:65 offset1:97
	ds_write2_b32 v119, v4, v36 offset0:130 offset1:162
	ds_write2_b32 v119, v5, v37 offset0:195 offset1:227
	v_add_u32_e32 v2, 0x800, v119
	ds_write2_b32 v2, v6, v38 offset0:8 offset1:40
	ds_write2_b32 v2, v7, v39 offset0:73 offset1:105
	ds_write2_b32 v2, v8, v40 offset0:138 offset1:170
	ds_write2_b32 v2, v9, v41 offset0:203 offset1:235
	v_add_u32_e32 v2, 0x1000, v119
	ds_write2_b32 v2, v10, v42 offset0:16 offset1:48
	ds_write2_b32 v2, v11, v43 offset0:81 offset1:113
	ds_write2_b32 v2, v12, v44 offset0:146 offset1:178
	ds_write2_b32 v2, v13, v45 offset0:211 offset1:243
	v_add_u32_e32 v2, 0x1800, v119
	ds_write2_b32 v2, v14, v46 offset0:24 offset1:56
	ds_write2_b32 v2, v15, v47 offset0:89 offset1:121
	ds_write2_b32 v2, v16, v48 offset0:154 offset1:186
	ds_write2_b32 v2, v17, v49 offset0:219 offset1:251
	v_add_u32_e32 v2, 0x2000, v119
	ds_write2_b32 v2, v18, v50 offset0:32 offset1:64
	ds_write2_b32 v2, v19, v51 offset0:97 offset1:129
	ds_write2_b32 v2, v20, v52 offset0:162 offset1:194
	v_add_u32_e32 v2, 0x2200, v119
	ds_write2_b32 v2, v21, v53 offset0:99 offset1:131
	v_add_u32_e32 v2, 0x2800, v119
	v_add_u32_e32 v66, s40, v112
	ds_write2_b32 v2, v22, v54 offset0:40 offset1:72
	ds_write2_b32 v2, v23, v55 offset0:105 offset1:137
	ds_write2_b32 v2, v24, v56 offset0:170 offset1:202
	v_add_u32_e32 v2, 0x2a00, v119
	v_ashrrev_i32_e32 v67, 31, v66
	v_readlane_b32 s4, v254, 23
	ds_write2_b32 v2, v25, v57 offset0:107 offset1:139
	v_add_u32_e32 v2, 0x3000, v119
	v_or_b32_e32 v68, s42, v113
	v_lshlrev_b64 v[70:71], 14, v[66:67]
	v_readlane_b32 s6, v254, 25
	v_readlane_b32 s7, v254, 26
	ds_write2_b32 v2, v26, v58 offset0:48 offset1:80
	ds_write2_b32 v2, v27, v59 offset0:113 offset1:145
	ds_write2_b32 v2, v28, v60 offset0:178 offset1:210
	v_add_u32_e32 v2, 0x3200, v119
	v_lshl_add_u64 v[70:71], s[6:7], 0, v[70:71]
	v_ashrrev_i32_e32 v69, 31, v68
	ds_write2_b32 v2, v29, v61 offset0:115 offset1:147
	v_add_u32_e32 v2, 0x3800, v119
	v_lshl_add_u64 v[68:69], v[68:69], 1, v[70:71]
	ds_write2_b32 v2, v30, v62 offset0:56 offset1:88
	ds_write2_b32 v2, v31, v63 offset0:121 offset1:153
	ds_write2_b32 v2, v32, v64 offset0:186 offset1:218
	v_add_u32_e32 v2, 0x3a00, v119
	s_mov_b32 s26, 1
	ds_write2_b32 v2, v33, v65 offset0:123 offset1:155
	v_lshl_add_u64 v[2:3], v[68:69], 0, v[0:1]
	v_lshl_add_u64 v[4:5], v[66:67], 2, s[28:29]
	s_mov_b32 s27, 0
	s_mov_b64 s[0:1], 0
	v_readlane_b32 s5, v254, 24
	s_waitcnt lgkmcnt(0)
	s_barrier

.LBB0_400:
	v_add_u32_e32 v77, s1, v66
	v_add_u32_e32 v90, s1, v71
	ds_read_b128 v[78:81], v77
	ds_read_b128 v[82:85], v90
	ds_read_b128 v[86:89], v90 offset:4608
	s_add_i32 s1, s1, 64
	s_cmpk_eq_i32 s1, 0x80
	s_waitcnt lgkmcnt(1)
	v_mfma_f32_32x32x16_bf16 v[2:17], v[78:81], v[82:85], v[2:17]
	s_waitcnt lgkmcnt(0)
	v_mfma_f32_32x32x16_bf16 v[34:49], v[78:81], v[86:89], v[34:49]
	ds_read_b128 v[78:81], v77 offset:4608
	s_waitcnt lgkmcnt(0)
	v_mfma_f32_32x32x16_bf16 v[18:33], v[78:81], v[82:85], v[18:33]
	v_mfma_f32_32x32x16_bf16 v[50:65], v[78:81], v[86:89], v[50:65]
	ds_read_b128 v[78:81], v77 offset:32
	ds_read_b128 v[82:85], v90 offset:32
	ds_read_b128 v[86:89], v90 offset:4640
	s_waitcnt lgkmcnt(1)
	v_mfma_f32_32x32x16_bf16 v[2:17], v[78:81], v[82:85], v[2:17]
	s_waitcnt lgkmcnt(0)
	v_mfma_f32_32x32x16_bf16 v[34:49], v[78:81], v[86:89], v[34:49]
	ds_read_b128 v[78:81], v77 offset:4640
	s_waitcnt lgkmcnt(0)
	v_mfma_f32_32x32x16_bf16 v[18:33], v[78:81], v[82:85], v[18:33]
	v_mfma_f32_32x32x16_bf16 v[50:65], v[78:81], v[86:89], v[50:65]
	s_cbranch_scc0 .LBB0_400
	s_barrier
	s_nop 5
	ds_write2_b32 v69, v2, v34 offset1:32
	ds_write2_b32 v69, v3, v35 offset0:65 offset1:97
	ds_write2_b32 v69, v4, v36 offset0:130 offset1:162
	ds_write2_b32 v69, v5, v37 offset0:195 offset1:227
	v_add_u32_e32 v2, 0x800, v69
	ds_write2_b32 v2, v6, v38 offset0:8 offset1:40
	ds_write2_b32 v2, v7, v39 offset0:73 offset1:105
	ds_write2_b32 v2, v8, v40 offset0:138 offset1:170
	ds_write2_b32 v2, v9, v41 offset0:203 offset1:235
	v_add_u32_e32 v2, 0x1000, v69
	ds_write2_b32 v2, v10, v42 offset0:16 offset1:48
	ds_write2_b32 v2, v11, v43 offset0:81 offset1:113
	ds_write2_b32 v2, v12, v44 offset0:146 offset1:178
	ds_write2_b32 v2, v13, v45 offset0:211 offset1:243
	v_add_u32_e32 v2, 0x1800, v69
	ds_write2_b32 v2, v14, v46 offset0:24 offset1:56
	ds_write2_b32 v2, v15, v47 offset0:89 offset1:121
	ds_write2_b32 v2, v16, v48 offset0:154 offset1:186
	ds_write2_b32 v2, v17, v49 offset0:219 offset1:251
	v_add_u32_e32 v2, 0x2000, v69
	ds_write2_b32 v2, v18, v50 offset0:32 offset1:64
	ds_write2_b32 v2, v19, v51 offset0:97 offset1:129
	ds_write2_b32 v2, v20, v52 offset0:162 offset1:194
	v_add_u32_e32 v2, 0x2200, v69
	ds_write2_b32 v2, v21, v53 offset0:99 offset1:131
	v_add_u32_e32 v2, 0x2800, v69
	ds_write2_b32 v2, v22, v54 offset0:40 offset1:72
	ds_write2_b32 v2, v23, v55 offset0:105 offset1:137
	ds_write2_b32 v2, v24, v56 offset0:170 offset1:202
	v_add_u32_e32 v2, 0x2a00, v69
	ds_write2_b32 v2, v25, v57 offset0:107 offset1:139
	v_add_u32_e32 v2, 0x3000, v69
	s_ashr_i32 s1, s27, 8
	ds_write2_b32 v2, v26, v58 offset0:48 offset1:80
	ds_write2_b32 v2, v27, v59 offset0:113 offset1:145
	ds_write2_b32 v2, v28, v60 offset0:178 offset1:210
	v_add_u32_e32 v2, 0x3200, v69
	s_add_i32 s1, s1, s20
	ds_write2_b32 v2, v29, v61 offset0:115 offset1:147
	v_add_u32_e32 v2, 0x3800, v69
	ds_write2_b32 v2, v30, v62 offset0:56 offset1:88
	ds_write2_b32 v2, v31, v63 offset0:121 offset1:153
	ds_write2_b32 v2, v32, v64 offset0:186 offset1:218
	v_add_u32_e32 v2, 0x3a00, v69
	s_cmpk_lt_i32 s1, 0x240
	ds_write2_b32 v2, v33, v65 offset0:123 offset1:155
	s_waitcnt lgkmcnt(0)
	s_barrier
	s_cbranch_scc0 .LBB0_398
	v_or_b32_e32 v2, s0, v67
	s_movk_i32 s0, 0xff
	v_cmp_lt_i32_e32 vcc, s0, v2
	s_and_saveexec_b64 s[0:1], vcc
	s_xor_b64 s[0:1], exec, s[0:1]
	v_add_u32_e32 v3, 0xffffff00, v2
	v_cvt_f32_u32_e32 v3, v3
	v_mul_f32_e32 v4, 0x3a001002, v3
	s_andn2_saveexec_b64 s[0:1], s[0:1]
	v_cvt_f32_i32_e32 v3, v2
	v_mul_f32_e32 v4, 0x3b808081, v3
	s_or_b64 exec, exec, s[0:1]
	s_lshl_b32 s0, s25, 7
	v_or_b32_e32 v5, s0, v72
	v_or_b32_e32 v6, s0, v0
	s_lshl_b32 s0, s26, 12
	v_subrev_u32_e32 v6, s0, v6
	v_and_b32_e32 v5, 0x3ff, v5
	v_and_b32_e32 v22, 63, v196
	v_add_u32_e32 v22, v5, v22
	v_cvt_f32_u32_e32 v22, v22
	s_mov_b32 s5, 0x447fc000
	v_mul_f32_e32 v22, 0x41447cbd, v22
	v_mov_b32_e32 v7, v70
	v_div_scale_f32 v9, s[26:27], s5, s5, v22
	v_rcp_f32_e32 v10, v9
	s_nop 0
	v_fma_f32 v11, -v9, v10, 1.0
	v_fmac_f32_e32 v10, v11, v10
	v_div_scale_f32 v11, vcc, v22, s5, v22
	v_mul_f32_e32 v13, v11, v10
	v_fma_f32 v14, -v9, v13, v11
	v_fmac_f32_e32 v13, v14, v10
	v_fma_f32 v9, -v9, v13, v11
	v_lshlrev_b32_e32 v21, 1, v2
	v_div_fmas_f32 v9, v9, v10, v13
	v_div_fixup_f32 v22, v9, s5, v22
	v_readfirstlane_b32 s0, v6
	v_readlane_b32 s28, v253, 34
	v_readlane_b32 s29, v253, 35
	v_sub_f32_e32 v20, 0xc0447cbd, v22
	s_mul_i32 s0, s0, 0x1200
	s_add_u32 s28, s28, s0
	s_addc_u32 s29, s29, 0
	s_add_u32 s40, s28, 0x900
	s_addc_u32 s41, s29, 0
	s_sub_u32 s28, s28, 0x1b00
	s_subb_u32 s29, s29, 0
	s_mov_b32 s0, 0
.LBB0_407:
	s_add_i32 s1, s0, 1
	s_add_i32 s4, s0, 2
	s_add_i32 s5, s0, 3
	v_readlane_b32 s26, v20, s0
	v_readlane_b32 s27, v20, s1
	v_readlane_b32 s6, v20, s4
	v_readlane_b32 s7, v20, s5
	ds_read2_b32 v[8:9], v7 offset1:65
	ds_read2_b32 v[10:11], v7 offset0:130 offset1:195
	v_add_u32_e32 v7, 0x410, v7
	v_mul_f32_e64 v12, |s26|, -v4
	v_mul_f32_e64 v13, |s27|, -v4
	v_mul_f32_e64 v14, |s6|, -v4
	v_mul_f32_e64 v15, |s7|, -v4
	v_mul_f32_e32 v12, 0x3fb8aa3b, v12
	v_mul_f32_e32 v13, 0x3fb8aa3b, v13
	v_mul_f32_e32 v14, 0x3fb8aa3b, v14
	v_mul_f32_e32 v15, 0x3fb8aa3b, v15
	v_exp_f32_e32 v12, v12
	v_exp_f32_e32 v13, v13
	v_exp_f32_e32 v14, v14
	v_exp_f32_e32 v15, v15
	s_add_i32 s0, s0, 4
	s_waitcnt lgkmcnt(0)
	v_mul_f32_e32 v8, v8, v12
	v_mul_f32_e32 v9, v9, v13
	v_mul_f32_e32 v10, v10, v14
	v_mul_f32_e32 v11, v11, v15
	v_cvt_pk_bf16_f32 v8, v8, v9
	v_cvt_pk_bf16_f32 v10, v10, v11
	s_cmp_lg_u32 s0, 64
	global_store_short v21, v8, s[28:29] offset:-2304
	global_store_short_d16_hi v21, v8, s[28:29] offset:2304
	global_store_short v21, v10, s[40:41] offset:-2304
	global_store_short_d16_hi v21, v10, s[40:41] offset:2304
	s_add_u32 s28, s28, 0x4800
	s_addc_u32 s29, s29, 0
	s_add_u32 s40, s40, 0x4800
	s_addc_u32 s41, s41, 0
	s_cmp_lg_u32 s0, 64
	s_cbranch_scc1 .LBB0_407
	s_branch .LBB0_398
